# G1 tile order rotated by 4 column panels (heavy k_r/q_r RoPE epilogues move from the first round to the last, so their imbalance no longer desynchronizes blocks for the remaining rounds)
# baseline (speedup 1.0000x reference)
.LBB0_35:
	s_or_b64 exec, exec, s[0:1]
	v_readlane_b32 s0, v251, 11
	v_readlane_b32 s1, v251, 12
	s_andn2_b64 vcc, exec, s[0:1]
	v_readlane_b32 s0, v253, 14
	v_readlane_b32 s52, v251, 0
	v_mov_b32_e32 v2, v213
	s_mov_b32 s2, s0
	s_add_i32 s2, s2, 4
	s_sub_i32 s3, s2, 23
	s_cmp_ge_i32 s2, 23
	s_cselect_b32 s2, s3, s2
	v_readlane_b32 s0, v253, 13
	v_readlane_b32 s53, v251, 1
	s_mov_b64 s[4:5], -1
	v_readfirstlane_b32 s22, v2
	s_mov_b32 s48, s0
	s_cbranch_vccnz .LBB0_39
	v_readlane_b32 s0, v253, 61
	v_readlane_b32 s1, v253, 62
	s_andn2_b64 vcc, exec, s[0:1]
	s_mov_b64 s[4:5], 0
	s_cbranch_vccnz .LBB0_38
	s_mov_b32 s48, 64
	s_mov_b64 s[4:5], -1

.LBB0_49:
	s_andn2_b64 vcc, exec, s[10:11]
	s_cbranch_vccnz .LBB0_51
	s_ashr_i32 s1, s0, 31
	s_lshr_b32 s1, s1, 29
	s_add_i32 s1, s0, s1
	s_ashr_i32 s3, s1, 3
	s_and_b32 s1, s1, -8
	s_sub_i32 s0, s0, s1
	s_cmp_lt_i32 s0, 0
	s_movk_i32 s1, 0xb9
	s_cselect_b32 s1, s1, 0xb8
	s_mul_i32 s0, s0, s1
	s_add_i32 s0, s0, s3
	s_mul_hi_i32 s1, s0, 0xb21642c9
	s_add_i32 s1, s1, s0
	s_lshr_b32 s3, s1, 31
	s_ashr_i32 s1, s1, 7
	s_add_i32 s1, s1, s3
	s_lshl_b32 s3, s1, 3
	s_sub_i32 s6, 64, s3
	s_min_i32 s6, s6, 8
	s_abs_i32 s7, s6
	v_cvt_f32_u32_e32 v2, s7
	s_sub_i32 s11, 0, s7
	s_mulk_i32 s1, 0xb8
	s_sub_i32 s0, s0, s1
	v_rcp_iflag_f32_e32 v2, v2
	s_abs_i32 s1, s0
	s_xor_b32 s10, s0, s6
	s_ashr_i32 s10, s10, 31
	v_mul_f32_e32 v2, 0x4f7ffffe, v2
	v_cvt_u32_f32_e32 v2, v2
	s_nop 0
	v_readfirstlane_b32 s16, v2
	s_mul_i32 s11, s11, s16
	s_mul_hi_u32 s11, s16, s11
	s_add_i32 s16, s16, s11
	s_mul_hi_u32 s11, s1, s16
	s_mul_i32 s16, s11, s7
	s_sub_i32 s1, s1, s16
	s_add_i32 s17, s11, 1
	s_sub_i32 s16, s1, s7
	s_cmp_ge_u32 s1, s7
	s_cselect_b32 s11, s17, s11
	s_cselect_b32 s1, s16, s1
	s_add_i32 s16, s11, 1
	s_cmp_ge_u32 s1, s7
	s_cselect_b32 s1, s16, s11
	s_xor_b32 s1, s1, s10
	s_sub_i32 s46, s1, s10
	s_mul_i32 s1, s46, s6
	s_sub_i32 s0, s0, s1
	s_add_i32 s72, s3, s0
	s_add_i32 s46, s46, 4
	s_sub_i32 s0, s46, 23
	s_cmp_ge_i32 s46, 23
	s_cselect_b32 s46, s0, s46
	s_mov_b64 s[6:7], -1
